# GEMM epilogue descriptor reload: seven LDS reads issued back to back (one round trip instead of two)
# speedup vs baseline: 1.0140x; 1.0010x over previous
; #define LAS __attribute__((address_space(3)))
;     DI void operator()(const f32x4 (&acc)[2][2][4][2], const Unit& u, int wr, int wc, int fr, int fq) const {
;     ...
;             const int rowt = row_off + u.pm * BM; const bool lat = rowt < MLAT;
;             const int vec = lat ? (rowt >> 13) : 8;
;             const float* bp = lat ? base_lat : base_ctx - (size_t)MLAT * DM; float* op = lat ? out_lat : out_ctx - (size_t)MLAT * DM;
;             const float* mrow = modp + (size_t)vec * 9216 + gate_chunk * 1024;
;             const int col0 = u.pn * BM + wc * 64 + 4 * fq;
;             f32x4 gv[2][2];
; #pragma unroll
;             for (int bj = 0; bj < 2; ++bj)
; #pragma unroll
;                 for (int n = 0; n < 2; ++n) gv[bj][n] = *(const GAS f32x4*)(mrow + col0 + bj * 32 + n * 16) * gs;
; #pragma unroll
;             for (int ai = 0; ai < 2; ++ai)
; #pragma unroll
;                 for (int m = 0; m < 4; ++m) { const size_t off = (size_t)(row0 + ai * HALF + m * 16) * DM + col0; f32x4 b[2][2];
; #pragma unroll
;                     for (int bj = 0; bj < 2; ++bj)
; #pragma unroll
;                         for (int n = 0; n < 2; ++n) b[bj][n] = *(const GAS f32x4*)(bp + off + bj * 32 + n * 16);
; #pragma unroll
;                     for (int bj = 0; bj < 2; ++bj)
; #pragma unroll
;                         for (int n = 0; n < 2; ++n) *(GAS f32x4*)(op + off + bj * 32 + n * 16) = b[bj][n] + gv[bj][n] * acc[ai][bj][m][n]; }
; DI Epi epi_load(LAS unsigned char* lds) {
;     const volatile LAS u32x4* p4 = (const volatile LAS u32x4*)(lds + CTL_EPI);
;     u32x4 q[7];
; #pragma unroll
;     for (int i = 0; i < 7; ++i) q[i] = p4[i];
;     unsigned w[28];
; #pragma unroll
;     for (int i = 0; i < 7; ++i) { w[4 * i] = __builtin_amdgcn_readfirstlane(q[i].x); w[4 * i + 1] = __builtin_amdgcn_readfirstlane(q[i].y); w[4 * i + 2] = __builtin_amdgcn_readfirstlane(q[i].z); w[4 * i + 3] = __builtin_amdgcn_readfirstlane(q[i].w); }
;     ...
;     Epi e;
;     e.mode = (int)w[0]; e.perm = w[1] != 0u; e.ldc = (int)w[2]; e.gate_chunk = (int)w[3]; e.gi = (int)w[4]; e.gs = __uint_as_float(w[5]);
;     e.O = (bf16_t*)W64(6); e.base_lat = (const float*)W64(8); e.base_ctx = (const float*)W64(10); e.out_lat = (float*)W64(12); e.out_ctx = (float*)W64(14);
;     e.modp = (const float*)W64(16); e.bias = (const float*)W64(18); e.BR = (bf16_t*)W64(20); e.MG = (bf16_t*)W64(22); e.row_off = (int)w[24];
.LBB0_796:
	v_readlane_b32 s0, v252, 38
	s_lshl_b32 s1, s41, 8
	s_mov_b64 s[82:83], -1
	v_mov_b32_e32 v158, s0
	v_mov_b32_e32 v159, s75
	v_mov_b32_e32 v160, s90
	v_mov_b32_e32 v161, s91
	v_mov_b32_e32 v162, s48
	v_mov_b32_e32 v163, s49
	v_mov_b32_e32 v164, s64
	ds_read_b128 v[130:133], v158
	ds_read_b128 v[134:137], v159
	ds_read_b128 v[138:141], v160
	ds_read_b128 v[142:145], v161
	ds_read_b128 v[146:149], v162
	ds_read_b128 v[150:153], v163
	ds_read_b128 v[154:157], v164
	s_waitcnt lgkmcnt(0)
	v_readfirstlane_b32 s55, v130
	v_readfirstlane_b32 s50, v132
	v_readfirstlane_b32 s33, v133
	s_waitcnt lgkmcnt(0)
	v_readfirstlane_b32 s46, v134
	v_readfirstlane_b32 s0, v154
	s_add_i32 s41, s0, s1
	v_readfirstlane_b32 s40, v135
	v_readfirstlane_b32 s30, v136
	v_readfirstlane_b32 s31, v137
	v_readfirstlane_b32 vcc_lo, v138
	v_readfirstlane_b32 vcc_hi, v139
	v_readfirstlane_b32 s58, v140
	v_readfirstlane_b32 s56, v141
	v_readfirstlane_b32 s72, v142
	v_readfirstlane_b32 s3, v143
	v_readfirstlane_b32 s57, v144
	v_readfirstlane_b32 s74, v145
	v_readfirstlane_b32 s76, v146
	v_readfirstlane_b32 s77, v147
	v_readfirstlane_b32 s80, v148
	v_readfirstlane_b32 s81, v149
	v_readfirstlane_b32 s44, v150
	v_readfirstlane_b32 s45, v151
	v_readfirstlane_b32 s34, v152
	v_readfirstlane_b32 s35, v153
	v_add_u32_e32 v176, s41, v183
	s_mov_b64 s[0:1], 0
	s_cmp_lt_i32 s55, 1
	s_mov_b64 s[6:7], 0
	s_cbranch_scc1 .LBB0_801
	s_cmp_gt_i32 s55, 1
	s_cbranch_scc0 .LBB0_808
	s_cmp_eq_u32 s55, 2
	s_mov_b64 s[6:7], -1
	s_cbranch_scc0 .LBB0_800
	s_min_i32 s6, s41, 0x10000
	s_ashr_i32 s6, s6, 13
	s_add_u32 s58, s58, 0xf0000000
	s_addc_u32 s56, s56, -1
	s_add_u32 s57, s57, 0xf0000000
	s_addc_u32 s74, s74, -1
	v_mul_hi_i32_i24_e32 v131, s6, v235
	v_mul_i32_i24_e32 v130, s6, v235
	s_lshl_b32 s6, s33, 10
	s_ashr_i32 s7, s6, 31
	v_lshl_add_u64 v[130:131], s[76:77], 0, v[130:131]
	s_lshl_b64 s[6:7], s[6:7], 2
	v_lshl_or_b32 v150, s51, 8, v185
	v_lshl_add_u64 v[130:131], v[130:131], 0, s[6:7]
	v_ashrrev_i32_e32 v151, 31, v150
	v_lshl_add_u64 v[164:165], v[150:151], 2, v[130:131]
	global_load_dwordx4 v[130:133], v[164:165], off
	global_load_dwordx4 v[134:137], v[164:165], off offset:64
	global_load_dwordx4 v[138:141], v[164:165], off offset:128
	global_load_dwordx4 v[142:145], v[164:165], off offset:192
	v_ashrrev_i32_e32 v177, 31, v176
	s_cmp_lt_i32 s41, 0x10000
	s_cselect_b32 s7, s3, s74
	s_cselect_b32 s6, s72, s57
	s_cselect_b32 vcc_hi, vcc_hi, s56
	s_cselect_b32 vcc_lo, vcc_lo, s58
	v_lshlrev_b64 v[146:147], 10, v[176:177]
	v_lshl_add_u64 v[146:147], v[146:147], 0, v[150:151]
	v_lshlrev_b64 v[146:147], 2, v[146:147]
	v_lshl_add_u64 v[178:179], vcc, 0, v[146:147]
	v_lshl_add_u64 v[180:181], s[6:7], 0, v[146:147]
	global_load_dwordx4 v[148:151], v[178:179], off
	global_load_dwordx4 v[152:155], v[178:179], off offset:64
	global_load_dwordx4 v[156:159], v[178:179], off offset:128
	global_load_dwordx4 v[160:163], v[178:179], off offset:192
	s_mov_b64 s[56:57], 0x10000
	v_lshl_add_u64 v[146:147], v[178:179], 0, s[56:57]
	v_lshl_add_u64 v[190:191], v[180:181], 0, s[56:57]
	global_load_dwordx4 v[236:239], v[146:147], off
	global_load_dwordx4 v[240:243], v[146:147], off offset:64
	global_load_dwordx4 v[244:247], v[146:147], off offset:128
	global_load_dwordx4 v[248:251], v[146:147], off offset:192
	s_mov_b64 s[56:57], 0x20000
	v_lshl_add_u64 v[146:147], v[178:179], 0, s[56:57]
	v_lshl_add_u64 v[208:209], v[180:181], 0, s[56:57]
	global_load_dwordx4 v[194:197], v[146:147], off
	global_load_dwordx4 v[200:203], v[146:147], off offset:64
	global_load_dwordx4 v[204:207], v[146:147], off offset:128
	global_load_dwordx4 v[230:233], v[146:147], off offset:192
	s_waitcnt vmcnt(12)
	v_pk_mul_f32 v[130:131], v[130:131], s[40:41] op_sel_hi:[1,0]
	v_pk_mul_f32 v[132:133], v[132:133], s[40:41] op_sel_hi:[1,0]
	v_pk_mul_f32 v[134:135], v[134:135], s[40:41] op_sel_hi:[1,0]
	v_pk_mul_f32 v[136:137], v[136:137], s[40:41] op_sel_hi:[1,0]
	v_pk_mul_f32 v[138:139], v[138:139], s[40:41] op_sel_hi:[1,0]
	v_pk_mul_f32 v[140:141], v[140:141], s[40:41] op_sel_hi:[1,0]
	v_pk_mul_f32 v[142:143], v[142:143], s[40:41] op_sel_hi:[1,0]
	v_pk_mul_f32 v[144:145], v[144:145], s[40:41] op_sel_hi:[1,0]
	s_waitcnt vmcnt(8)
	v_pk_fma_f32 v[148:149], v[122:123], v[130:131], v[148:149]
	v_pk_fma_f32 v[150:151], v[124:125], v[132:133], v[150:151]
	v_pk_fma_f32 v[152:153], v[126:127], v[134:135], v[152:153]
	v_pk_fma_f32 v[154:155], v[128:129], v[136:137], v[154:155]
	v_pk_fma_f32 v[156:157], v[118:119], v[138:139], v[156:157]
	v_pk_fma_f32 v[158:159], v[120:121], v[140:141], v[158:159]
	v_pk_fma_f32 v[160:161], v[114:115], v[142:143], v[160:161]
	v_pk_fma_f32 v[162:163], v[116:117], v[144:145], v[162:163]
	global_store_dwordx4 v[180:181], v[148:151], off
	global_store_dwordx4 v[180:181], v[152:155], off offset:64
	global_store_dwordx4 v[180:181], v[156:159], off offset:128
	global_store_dwordx4 v[180:181], v[160:163], off offset:192
	s_mov_b64 s[56:57], 0x30000
	v_lshl_add_u64 v[146:147], v[178:179], 0, s[56:57]
	v_lshl_add_u64 v[164:165], v[180:181], 0, s[56:57]
	global_load_dwordx4 v[148:151], v[146:147], off
	global_load_dwordx4 v[152:155], v[146:147], off offset:64
	global_load_dwordx4 v[156:159], v[146:147], off offset:128
	global_load_dwordx4 v[160:163], v[146:147], off offset:192
	s_waitcnt vmcnt(12)
; #define GAS __attribute__((address_space(1)))
;     DI void operator()(const f32x4 (&acc)[2][2][4][2], const Unit& u, int wr, int wc, int fr, int fq) const {
;     ...
; #pragma unroll
;             for (int ai = 0; ai < 2; ++ai)
; #pragma unroll
;                 for (int m = 0; m < 4; ++m) { const size_t off = (size_t)(row0 + ai * HALF + m * 16) * DM + col0; f32x4 b[2][2];
; #pragma unroll
;                     for (int bj = 0; bj < 2; ++bj)
; #pragma unroll
;                         for (int n = 0; n < 2; ++n) b[bj][n] = *(const GAS f32x4*)(bp + off + bj * 32 + n * 16);
; #pragma unroll
;                     for (int bj = 0; bj < 2; ++bj)
; #pragma unroll
;                         for (int n = 0; n < 2; ++n) *(GAS f32x4*)(op + off + bj * 32 + n * 16) = b[bj][n] + gv[bj][n] * acc[ai][bj][m][n]; }
	v_pk_fma_f32 v[236:237], v[110:111], v[130:131], v[236:237]
	v_pk_fma_f32 v[238:239], v[112:113], v[132:133], v[238:239]
	v_pk_fma_f32 v[240:241], v[106:107], v[134:135], v[240:241]
	v_pk_fma_f32 v[242:243], v[108:109], v[136:137], v[242:243]
	v_pk_fma_f32 v[244:245], v[102:103], v[138:139], v[244:245]
	v_pk_fma_f32 v[246:247], v[104:105], v[140:141], v[246:247]
	v_pk_fma_f32 v[248:249], v[98:99], v[142:143], v[248:249]
	v_pk_fma_f32 v[250:251], v[100:101], v[144:145], v[250:251]
	global_store_dwordx4 v[190:191], v[236:239], off
	global_store_dwordx4 v[190:191], v[240:243], off offset:64
	global_store_dwordx4 v[190:191], v[244:247], off offset:128
	global_store_dwordx4 v[190:191], v[248:251], off offset:192
	s_mov_b64 s[56:57], 0x80000
	v_lshl_add_u64 v[146:147], v[178:179], 0, s[56:57]
	v_lshl_add_u64 v[190:191], v[180:181], 0, s[56:57]
	global_load_dwordx4 v[236:239], v[146:147], off
	global_load_dwordx4 v[240:243], v[146:147], off offset:64
	global_load_dwordx4 v[244:247], v[146:147], off offset:128
	global_load_dwordx4 v[248:251], v[146:147], off offset:192
	s_waitcnt vmcnt(16)
	v_pk_fma_f32 v[194:195], v[94:95], v[130:131], v[194:195]
	v_pk_fma_f32 v[196:197], v[96:97], v[132:133], v[196:197]
	v_pk_fma_f32 v[200:201], v[90:91], v[134:135], v[200:201]
	v_pk_fma_f32 v[202:203], v[92:93], v[136:137], v[202:203]
	v_pk_fma_f32 v[204:205], v[86:87], v[138:139], v[204:205]
	v_pk_fma_f32 v[206:207], v[88:89], v[140:141], v[206:207]
	v_pk_fma_f32 v[230:231], v[82:83], v[142:143], v[230:231]
	v_pk_fma_f32 v[232:233], v[84:85], v[144:145], v[232:233]
	global_store_dwordx4 v[208:209], v[194:197], off
	global_store_dwordx4 v[208:209], v[200:203], off offset:64
	global_store_dwordx4 v[208:209], v[204:207], off offset:128
	global_store_dwordx4 v[208:209], v[230:233], off offset:192
	s_mov_b64 s[56:57], 0x90000
	v_lshl_add_u64 v[146:147], v[178:179], 0, s[56:57]
	v_lshl_add_u64 v[208:209], v[180:181], 0, s[56:57]
	global_load_dwordx4 v[194:197], v[146:147], off
	global_load_dwordx4 v[200:203], v[146:147], off offset:64
	global_load_dwordx4 v[204:207], v[146:147], off offset:128
	global_load_dwordx4 v[230:233], v[146:147], off offset:192
	s_waitcnt vmcnt(16)
	v_pk_fma_f32 v[148:149], v[78:79], v[130:131], v[148:149]
	v_pk_fma_f32 v[150:151], v[80:81], v[132:133], v[150:151]
	v_pk_fma_f32 v[152:153], v[74:75], v[134:135], v[152:153]
	v_pk_fma_f32 v[154:155], v[76:77], v[136:137], v[154:155]
	v_pk_fma_f32 v[156:157], v[70:71], v[138:139], v[156:157]
	v_pk_fma_f32 v[158:159], v[72:73], v[140:141], v[158:159]
	v_pk_fma_f32 v[160:161], v[66:67], v[142:143], v[160:161]
	v_pk_fma_f32 v[162:163], v[68:69], v[144:145], v[162:163]
	global_store_dwordx4 v[164:165], v[148:151], off
	global_store_dwordx4 v[164:165], v[152:155], off offset:64
	global_store_dwordx4 v[164:165], v[156:159], off offset:128
	global_store_dwordx4 v[164:165], v[160:163], off offset:192
	s_mov_b64 s[56:57], 0xa0000
	v_lshl_add_u64 v[146:147], v[178:179], 0, s[56:57]
	v_lshl_add_u64 v[164:165], v[180:181], 0, s[56:57]
	global_load_dwordx4 v[148:151], v[146:147], off
	global_load_dwordx4 v[152:155], v[146:147], off offset:64
	global_load_dwordx4 v[156:159], v[146:147], off offset:128
	global_load_dwordx4 v[160:163], v[146:147], off offset:192
	s_waitcnt vmcnt(16)
	v_pk_fma_f32 v[236:237], v[62:63], v[130:131], v[236:237]
	v_pk_fma_f32 v[238:239], v[64:65], v[132:133], v[238:239]
	v_pk_fma_f32 v[240:241], v[58:59], v[134:135], v[240:241]
	v_pk_fma_f32 v[242:243], v[60:61], v[136:137], v[242:243]
	v_pk_fma_f32 v[244:245], v[54:55], v[138:139], v[244:245]
	v_pk_fma_f32 v[246:247], v[56:57], v[140:141], v[246:247]
	v_pk_fma_f32 v[248:249], v[50:51], v[142:143], v[248:249]
	v_pk_fma_f32 v[250:251], v[52:53], v[144:145], v[250:251]
	global_store_dwordx4 v[190:191], v[236:239], off
	global_store_dwordx4 v[190:191], v[240:243], off offset:64
	global_store_dwordx4 v[190:191], v[244:247], off offset:128
	global_store_dwordx4 v[190:191], v[248:251], off offset:192
	s_mov_b64 s[56:57], 0xb0000
	v_lshl_add_u64 v[146:147], v[178:179], 0, s[56:57]
	v_lshl_add_u64 v[190:191], v[180:181], 0, s[56:57]
	global_load_dwordx4 v[236:239], v[146:147], off
	global_load_dwordx4 v[240:243], v[146:147], off offset:64
	global_load_dwordx4 v[244:247], v[146:147], off offset:128
	global_load_dwordx4 v[248:251], v[146:147], off offset:192
	s_waitcnt vmcnt(16)
	v_pk_fma_f32 v[194:195], v[46:47], v[130:131], v[194:195]
	v_pk_fma_f32 v[196:197], v[48:49], v[132:133], v[196:197]
	v_pk_fma_f32 v[200:201], v[42:43], v[134:135], v[200:201]
	v_pk_fma_f32 v[202:203], v[44:45], v[136:137], v[202:203]
	v_pk_fma_f32 v[204:205], v[38:39], v[138:139], v[204:205]
	v_pk_fma_f32 v[206:207], v[40:41], v[140:141], v[206:207]
	v_pk_fma_f32 v[230:231], v[34:35], v[142:143], v[230:231]
	v_pk_fma_f32 v[232:233], v[36:37], v[144:145], v[232:233]
	global_store_dwordx4 v[208:209], v[194:197], off
	global_store_dwordx4 v[208:209], v[200:203], off offset:64
	global_store_dwordx4 v[208:209], v[204:207], off offset:128
	global_store_dwordx4 v[208:209], v[230:233], off offset:192
	s_waitcnt vmcnt(12)
	v_pk_fma_f32 v[148:149], v[30:31], v[130:131], v[148:149]
	v_pk_fma_f32 v[150:151], v[32:33], v[132:133], v[150:151]
	v_pk_fma_f32 v[152:153], v[26:27], v[134:135], v[152:153]
	v_pk_fma_f32 v[154:155], v[28:29], v[136:137], v[154:155]
	v_pk_fma_f32 v[156:157], v[22:23], v[138:139], v[156:157]
	v_pk_fma_f32 v[158:159], v[24:25], v[140:141], v[158:159]
	v_pk_fma_f32 v[160:161], v[18:19], v[142:143], v[160:161]
	v_pk_fma_f32 v[162:163], v[20:21], v[144:145], v[162:163]
	global_store_dwordx4 v[164:165], v[148:151], off
	global_store_dwordx4 v[164:165], v[152:155], off offset:64
	global_store_dwordx4 v[164:165], v[156:159], off offset:128
	global_store_dwordx4 v[164:165], v[160:163], off offset:192
	s_waitcnt vmcnt(8)
	v_pk_fma_f32 v[236:237], v[14:15], v[130:131], v[236:237]
	v_pk_fma_f32 v[238:239], v[16:17], v[132:133], v[238:239]
	v_pk_fma_f32 v[240:241], v[10:11], v[134:135], v[240:241]
	v_pk_fma_f32 v[242:243], v[12:13], v[136:137], v[242:243]
	v_pk_fma_f32 v[244:245], v[6:7], v[138:139], v[244:245]
	v_pk_fma_f32 v[246:247], v[8:9], v[140:141], v[246:247]
	v_pk_fma_f32 v[248:249], v[2:3], v[142:143], v[248:249]
	v_pk_fma_f32 v[250:251], v[4:5], v[144:145], v[250:251]
	global_store_dwordx4 v[190:191], v[236:239], off
	global_store_dwordx4 v[190:191], v[240:243], off offset:64
	global_store_dwordx4 v[190:191], v[244:247], off offset:128
	global_store_dwordx4 v[190:191], v[248:251], off offset:192
	s_mov_b64 s[56:57], 0xb0000
	s_mov_b64 s[6:7], 0
